# static s_setprio 1 for waves 4-7 during the attention fast path
# speedup vs baseline: 1.0015x; 1.0015x over previous
.Lmy_attn:
	s_mov_b64 exec, -1
	s_mov_b32 s51, m0
	s_add_u32 s8, s12, 0x5800000
	s_addc_u32 s9, s13, 0
	s_add_u32 s20, s12, 0x7000000
	s_addc_u32 s21, s13, 0
	s_add_u32 s34, s12, 0x7800000
	s_addc_u32 s35, s13, 0
	v_and_b32_e32 v190, 63, v210
	v_readfirstlane_b32 s2, v210
	s_nop 3
	s_lshr_b32 s2, s2, 6
	s_lshl_b32 s31, s2, 10
	s_add_i32 s48, s31, 0x2000
	s_add_i32 s49, s31, 0x4000
	s_add_i32 s40, s31, 24576
	s_add_i32 s54, s31, 32768
	s_add_i32 s55, s31, 40960
	v_lshrrev_b32_e32 v0, 5, v190
	v_and_b32_e32 v1, 31, v190
	v_lshlrev_b32_e32 v2, 4, v1
	v_lshl_or_b32 v231, v0, 10, v2
	v_mul_u32_u24_e32 v2, 0x600, v1
	v_lshl_add_u32 v209, v0, 4, v2
	v_bfe_u32 v2, v190, 4, 1
	v_lshlrev_b32_e32 v2, 5, v2
	v_and_b32_e32 v3, 3, v190
	v_lshl_add_u32 v2, v3, 3, v2
	v_bfe_u32 v3, v190, 2, 2
	v_lshl_add_u32 v3, v0, 2, v3
	v_lshl_add_u32 v2, v3, 6, v2
	v_add_u32_e32 v230, 24576, v2
	s_lshl_b32 s6, s2, 4
	v_lshl_add_u32 v232, v190, 9, s6
	s_and_b32 s6, s2, 3
	s_lshl_b32 s6, s6, 13
	s_lshr_b32 s7, s2, 2
	s_lshl_b32 s7, s7, 6
	s_add_i32 s6, s6, s7
	v_lshrrev_b32_e32 v2, 2, v190
	v_and_b32_e32 v3, 3, v190
	v_lshlrev_b32_e32 v3, 4, v3
	v_lshl_add_u32 v2, v2, 9, v3
	v_add_u32_e32 v233, s6, v2
	v_and_b32_e32 v2, 15, v190
	v_bfe_u32 v3, v190, 4, 1
	v_cmp_eq_u32_e32 vcc, v2, v3
	v_mov_b32_e32 v4, 0x3f803f80
	s_nop 1
	v_cndmask_b32_e32 v226, 0, v4, vcc
	v_cndmask_b32_e32 v227, 0, v4, vcc
	v_cndmask_b32_e32 v228, 0, v4, vcc
	v_cndmask_b32_e32 v229, 0, v4, vcc
	v_readlane_b32 s41, v253, 2
	s_nop 3
	s_cmp_ge_u32 s2, 4
	s_cbranch_scc0 .Lmy_noprio
	s_setprio 1
.Lmy_noprio:
	s_and_b32 s6, s41, 31
	s_bfe_u32 s7, s41, 0x30005
	s_lshr_b32 s12, s41, 8
	s_lshr_b32 s13, s7, 2
	s_and_b32 s7, s7, 3
	s_mul_i32 s30, s7, 3
	s_add_i32 s30, s30, s12
	s_lshl_b32 s13, s13, 13
	s_lshl_b32 s6, s6, 8
	s_add_i32 s6, s6, s13
	s_lshl_b32 s12, s2, 5
	s_add_i32 s6, s6, s12
	s_mul_i32 s12, s6, 0x600
	s_lshl_b32 s30, s30, 7
	s_add_i32 s12, s12, s30
	s_add_u32 s44, s8, s12
	s_addc_u32 s45, s9, 0
	s_lshl_b32 s12, s6, 11
	s_add_i32 s12, s12, s30
	s_add_u32 s46, s14, s12
	s_addc_u32 s47, s15, 0
	s_lshl_b32 s12, s13, 9
	s_lshl_b32 s30, s7, 7
	s_add_i32 s12, s12, s30
	s_add_u32 s36, s20, s12
	s_addc_u32 s37, s21, 0
	s_add_u32 s38, s34, s12
	s_addc_u32 s39, s35, 0
	global_load_dwordx4 v[32:35], v209, s[44:45] offset:0
	global_load_dwordx4 v[36:39], v209, s[44:45] offset:32
	global_load_dwordx4 v[40:43], v209, s[44:45] offset:64
	global_load_dwordx4 v[44:47], v209, s[44:45] offset:96
	s_mov_b32 m0, s31
	s_nop 0
	global_load_lds_dwordx4 v232, s[36:37]
	s_mov_b32 m0, s40
	s_nop 0
	global_load_lds_dwordx4 v233, s[38:39]
	s_add_u32 s42, s36, 0x8000
	s_addc_u32 s43, s37, 0
	s_mov_b32 m0, s48
	s_nop 0
	global_load_lds_dwordx4 v232, s[42:43]
	s_add_u32 s42, s36, 0x10000
	s_addc_u32 s43, s37, 0
	s_mov_b32 m0, s49
	s_nop 0
	global_load_lds_dwordx4 v232, s[42:43]

.Lmy_nopf:
	ds_read_b64_tr_b16 v[80:81], v230 offset:8192
	ds_read_b64_tr_b16 v[82:83], v230 offset:8704
	ds_read_b64_tr_b16 v[96:97], v230 offset:12288
	ds_read_b64_tr_b16 v[98:99], v230 offset:12800
	v_exp_f32_e32 v160, v160
	v_exp_f32_e32 v161, v161
	v_cvt_pk_bf16_f32 v176, v144, v145
	v_cvt_pk_bf16_f32 v177, v146, v147
	ds_read_b64_tr_b16 v[84:85], v230 offset:9216
	ds_read_b64_tr_b16 v[86:87], v230 offset:9728
	ds_read_b64_tr_b16 v[100:101], v230 offset:13312
	ds_read_b64_tr_b16 v[102:103], v230 offset:13824
	v_exp_f32_e32 v162, v162
	v_exp_f32_e32 v163, v163
	v_cvt_pk_bf16_f32 v178, v148, v149
	v_cvt_pk_bf16_f32 v179, v150, v151
	ds_read_b64_tr_b16 v[88:89], v230 offset:10240
	ds_read_b64_tr_b16 v[90:91], v230 offset:10752
	ds_read_b64_tr_b16 v[104:105], v230 offset:14336
	ds_read_b64_tr_b16 v[106:107], v230 offset:14848
	v_exp_f32_e32 v164, v164
	v_exp_f32_e32 v165, v165
	v_cvt_pk_bf16_f32 v180, v152, v153
	v_cvt_pk_bf16_f32 v181, v154, v155
	ds_read_b64_tr_b16 v[92:93], v230 offset:11264
	ds_read_b64_tr_b16 v[94:95], v230 offset:11776
	ds_read_b64_tr_b16 v[108:109], v230 offset:15360
	ds_read_b64_tr_b16 v[110:111], v230 offset:15872
	v_exp_f32_e32 v166, v166
	v_exp_f32_e32 v167, v167
	v_cvt_pk_bf16_f32 v182, v156, v157
	v_cvt_pk_bf16_f32 v183, v158, v159
	v_exp_f32_e32 v168, v168
	v_exp_f32_e32 v169, v169
	v_cvt_pk_bf16_f32 v184, v160, v161
	v_cvt_pk_bf16_f32 v185, v162, v163
	v_exp_f32_e32 v170, v170
	v_exp_f32_e32 v171, v171
	v_cvt_pk_bf16_f32 v186, v164, v165
	v_cvt_pk_bf16_f32 v187, v166, v167
	v_exp_f32_e32 v172, v172
	v_exp_f32_e32 v173, v173
	v_exp_f32_e32 v174, v174
	v_cvt_pk_bf16_f32 v204, v168, v169
	v_exp_f32_e32 v175, v175
	v_cvt_pk_bf16_f32 v205, v170, v171
	v_cvt_pk_bf16_f32 v206, v172, v173
	v_cvt_pk_bf16_f32 v207, v174, v175
	s_waitcnt lgkmcnt(0)
	v_mfma_f32_32x32x16_bf16 v[0:15], v[176:179], v[80:83], v[0:15]
	v_mfma_f32_32x32x16_bf16 v[16:31], v[176:179], v[96:99], v[16:31]
	v_mfma_f32_16x16x32_bf16 v[222:225], v[176:179], v[226:229], v[222:225]
	v_mfma_f32_32x32x16_bf16 v[0:15], v[180:183], v[84:87], v[0:15]
	v_mfma_f32_32x32x16_bf16 v[16:31], v[180:183], v[100:103], v[16:31]
	v_mfma_f32_16x16x32_bf16 v[222:225], v[180:183], v[226:229], v[222:225]
	v_mfma_f32_32x32x16_bf16 v[0:15], v[184:187], v[88:91], v[0:15]
	v_mfma_f32_32x32x16_bf16 v[16:31], v[184:187], v[104:107], v[16:31]
	v_mfma_f32_16x16x32_bf16 v[222:225], v[184:187], v[226:229], v[222:225]
	v_mfma_f32_32x32x16_bf16 v[0:15], v[204:207], v[92:95], v[0:15]
	v_mfma_f32_32x32x16_bf16 v[16:31], v[204:207], v[108:111], v[16:31]
	v_mfma_f32_16x16x32_bf16 v[222:225], v[204:207], v[226:229], v[222:225]
	s_lshl_b32 s6, s2, 8
	s_add_i32 s6, s6, 49152
	v_and_b32_e32 v112, 15, v190
	v_lshrrev_b32_e32 v113, 4, v190
	v_lshlrev_b32_e32 v114, 6, v112
	v_lshl_add_u32 v114, v113, 4, v114
	v_add_u32_e32 v114, s6, v114
	v_cmp_gt_u32_e32 vcc, 2, v112
	s_and_saveexec_b64 s[12:13], vcc
	ds_write_b128 v114, v[222:225]
	s_mov_b64 exec, s[12:13]
	v_lshrrev_b32_e32 v115, 5, v190
	v_lshl_add_u32 v115, v115, 4, s6
	ds_read_b128 v[128:131], v115 offset:0
	ds_read_b128 v[132:135], v115 offset:32
	ds_read_b128 v[136:139], v115 offset:64
	ds_read_b128 v[140:143], v115 offset:96
	s_waitcnt lgkmcnt(3)
	v_rcp_f32_e32 v128, v128
	v_rcp_f32_e32 v129, v129
	v_rcp_f32_e32 v130, v130
	v_rcp_f32_e32 v131, v131
	s_waitcnt lgkmcnt(2)
	v_rcp_f32_e32 v132, v132
	v_rcp_f32_e32 v133, v133
	v_rcp_f32_e32 v134, v134
	v_rcp_f32_e32 v135, v135
	s_waitcnt lgkmcnt(1)
	v_rcp_f32_e32 v136, v136
	v_rcp_f32_e32 v137, v137
	v_rcp_f32_e32 v138, v138
	v_rcp_f32_e32 v139, v139
	s_waitcnt lgkmcnt(0)
	v_rcp_f32_e32 v140, v140
	v_rcp_f32_e32 v141, v141
	v_rcp_f32_e32 v142, v142
	v_rcp_f32_e32 v143, v143
	s_lshl_b32 s7, s2, 12
	s_add_i32 s7, s7, 51200
	v_lshrrev_b32_e32 v112, 5, v190
	v_and_b32_e32 v113, 31, v190
	v_lshlrev_b32_e32 v113, 1, v113
	v_lshl_add_u32 v112, v112, 9, v113
	v_add_u32_e32 v112, s7, v112
	v_mul_f32_e32 v0, v0, v128
	v_cvt_pk_bf16_f32 v0, v0, v0
	ds_write_b16 v112, v0 offset:0
	v_mul_f32_e32 v16, v16, v128
	v_cvt_pk_bf16_f32 v16, v16, v16
	ds_write_b16 v112, v16 offset:64
	v_mul_f32_e32 v1, v1, v129
	v_cvt_pk_bf16_f32 v1, v1, v1
	ds_write_b16 v112, v1 offset:128
	v_mul_f32_e32 v17, v17, v129
	v_cvt_pk_bf16_f32 v17, v17, v17
	ds_write_b16 v112, v17 offset:192
	v_mul_f32_e32 v2, v2, v130
	v_cvt_pk_bf16_f32 v2, v2, v2
	ds_write_b16 v112, v2 offset:256
	v_mul_f32_e32 v18, v18, v130
	v_cvt_pk_bf16_f32 v18, v18, v18
	ds_write_b16 v112, v18 offset:320
	v_mul_f32_e32 v3, v3, v131
	v_cvt_pk_bf16_f32 v3, v3, v3
	ds_write_b16 v112, v3 offset:384
	v_mul_f32_e32 v19, v19, v131
	v_cvt_pk_bf16_f32 v19, v19, v19
	ds_write_b16 v112, v19 offset:448
	v_mul_f32_e32 v4, v4, v132
	v_cvt_pk_bf16_f32 v4, v4, v4
	ds_write_b16 v112, v4 offset:1024
	v_mul_f32_e32 v20, v20, v132
	v_cvt_pk_bf16_f32 v20, v20, v20
	ds_write_b16 v112, v20 offset:1088
	v_mul_f32_e32 v5, v5, v133
	v_cvt_pk_bf16_f32 v5, v5, v5
	ds_write_b16 v112, v5 offset:1152
	v_mul_f32_e32 v21, v21, v133
	v_cvt_pk_bf16_f32 v21, v21, v21
	ds_write_b16 v112, v21 offset:1216
	v_mul_f32_e32 v6, v6, v134
	v_cvt_pk_bf16_f32 v6, v6, v6
	ds_write_b16 v112, v6 offset:1280
	v_mul_f32_e32 v22, v22, v134
	v_cvt_pk_bf16_f32 v22, v22, v22
	ds_write_b16 v112, v22 offset:1344
	v_mul_f32_e32 v7, v7, v135
	v_cvt_pk_bf16_f32 v7, v7, v7
	ds_write_b16 v112, v7 offset:1408
	v_mul_f32_e32 v23, v23, v135
	v_cvt_pk_bf16_f32 v23, v23, v23
	ds_write_b16 v112, v23 offset:1472
	v_mul_f32_e32 v8, v8, v136
	v_cvt_pk_bf16_f32 v8, v8, v8
	ds_write_b16 v112, v8 offset:2048
	v_mul_f32_e32 v24, v24, v136
	v_cvt_pk_bf16_f32 v24, v24, v24
	ds_write_b16 v112, v24 offset:2112
	v_mul_f32_e32 v9, v9, v137
	v_cvt_pk_bf16_f32 v9, v9, v9
	ds_write_b16 v112, v9 offset:2176
	v_mul_f32_e32 v25, v25, v137
	v_cvt_pk_bf16_f32 v25, v25, v25
	ds_write_b16 v112, v25 offset:2240
	v_mul_f32_e32 v10, v10, v138
	v_cvt_pk_bf16_f32 v10, v10, v10
	ds_write_b16 v112, v10 offset:2304
	v_mul_f32_e32 v26, v26, v138
	v_cvt_pk_bf16_f32 v26, v26, v26
	ds_write_b16 v112, v26 offset:2368
	v_mul_f32_e32 v11, v11, v139
	v_cvt_pk_bf16_f32 v11, v11, v11
	ds_write_b16 v112, v11 offset:2432
	v_mul_f32_e32 v27, v27, v139
	v_cvt_pk_bf16_f32 v27, v27, v27
	ds_write_b16 v112, v27 offset:2496
	v_mul_f32_e32 v12, v12, v140
	v_cvt_pk_bf16_f32 v12, v12, v12
	ds_write_b16 v112, v12 offset:3072
	v_mul_f32_e32 v28, v28, v140
	v_cvt_pk_bf16_f32 v28, v28, v28
	ds_write_b16 v112, v28 offset:3136
	v_mul_f32_e32 v13, v13, v141
	v_cvt_pk_bf16_f32 v13, v13, v13
	ds_write_b16 v112, v13 offset:3200
	v_mul_f32_e32 v29, v29, v141
	v_cvt_pk_bf16_f32 v29, v29, v29
	ds_write_b16 v112, v29 offset:3264
	v_mul_f32_e32 v14, v14, v142
	v_cvt_pk_bf16_f32 v14, v14, v14
	ds_write_b16 v112, v14 offset:3328
	v_mul_f32_e32 v30, v30, v142
	v_cvt_pk_bf16_f32 v30, v30, v30
	ds_write_b16 v112, v30 offset:3392
	v_mul_f32_e32 v15, v15, v143
	v_cvt_pk_bf16_f32 v15, v15, v15
	ds_write_b16 v112, v15 offset:3456
	v_mul_f32_e32 v31, v31, v143
	v_cvt_pk_bf16_f32 v31, v31, v31
	ds_write_b16 v112, v31 offset:3520
	v_lshrrev_b32_e32 v113, 3, v190
	v_and_b32_e32 v114, 7, v190
	v_lshlrev_b32_e32 v114, 4, v114
	v_lshl_add_u32 v115, v113, 7, v114
	v_add_u32_e32 v115, s7, v115
	v_lshl_add_u32 v116, v113, 11, v114
	s_waitcnt lgkmcnt(0)
	ds_read_b128 v[144:147], v115 offset:0
	ds_read_b128 v[148:151], v115 offset:1024
	ds_read_b128 v[152:155], v115 offset:2048
	ds_read_b128 v[156:159], v115 offset:3072
	s_waitcnt lgkmcnt(3)
	global_store_dwordx4 v116, v[144:147], s[46:47]
	s_nop 1
	v_add_u32_e32 v116, 0x4000, v116
	s_waitcnt lgkmcnt(2)
	global_store_dwordx4 v116, v[148:151], s[46:47]
	s_nop 1
	v_add_u32_e32 v116, 0x4000, v116
	s_waitcnt lgkmcnt(1)
	global_store_dwordx4 v116, v[152:155], s[46:47]
	s_nop 1
	v_add_u32_e32 v116, 0x4000, v116
	s_waitcnt lgkmcnt(0)
	global_store_dwordx4 v116, v[156:159], s[46:47]
	s_nop 1
	s_waitcnt lgkmcnt(0)
	s_barrier
	s_mov_b64 s[46:47], s[56:57]
	s_add_i32 s41, s41, s16
	s_cmpk_lt_i32 s41, 0x300
	s_cbranch_scc1 .Lmy_unit
	s_mov_b32 m0, s51
	s_setprio 0
	s_branch .LBB0_274
